# adds DPP wave min-max reduction in select (replaces 12 ds_bpermute hops) on top of v19
# speedup vs baseline: 1.0060x; 1.0060x over previous
; DI unsigned fkey(float f) { unsigned u = __float_as_uint(f); return (u & 0x80000000u) ? ~u : (u | 0x80000000u); }
; template <int NR>
; DI u64 select_wave(float* scw, int nreg, int lane) {
;   unsigned key[NR];
;   unsigned kmin = 0xffffffffu, kmax = 0u;
; #pragma unroll
;   for (int r = 0; r < NR; ++r) {
;     const unsigned k = fkey(scw[64 * r + lane]);
;     const bool ok = r < nreg;
;     key[r] = ok ? k : 0u;
;     kmin = min(kmin, ok ? k : 0xffffffffu); kmax = max(kmax, key[r]);
;   }
; DI void dsa_select_item(const Params& P, int it, float* sc, int wave, int lane) {
;     ...
;   if (N > 256) {
;     float* scw = sc + wave * SC_STRIDE;
;     if (nreg <= 8) myword = select_wave<8>(scw, nreg, lane);
;     else if (nreg <= 16) myword = select_wave<16>(scw, nreg, lane);
;     else if (nreg <= 24) myword = select_wave<24>(scw, nreg, lane);
;     else if (nreg <= 32) myword = select_wave<32>(scw, nreg, lane);
;     else if (nreg <= 48) myword = select_wave<48>(scw, nreg, lane);
;     else myword = select_wave<64>(scw, nreg, lane);
.LBB0_204:
	s_waitcnt vmcnt(11)
	v_mov_b64_e32 v[26:27], -1
	s_andn2_b64 vcc, exec, s[0:1]
	s_waitcnt lgkmcnt(0)
	s_barrier
	s_cbranch_vccnz .LBB0_759
	s_cmpk_gt_u32 s28, 0x1ff
	s_mov_b64 s[0:1], -1
	s_cbranch_scc0 .LBB0_733
	s_cmpk_gt_u32 s28, 0x3ff
	s_cbranch_scc0 .LBB0_670
	s_cmpk_gt_u32 s28, 0x5ff
	s_cbranch_scc0 .LBB0_591
	s_cmpk_gt_u32 s28, 0x7ff
	s_cbranch_scc0 .LBB0_496
	ds_read2st64_b32 v[2:3], v87 offset1:1
	ds_read2st64_b32 v[4:5], v87 offset0:2 offset1:3
	ds_read2st64_b32 v[6:7], v87 offset0:4 offset1:5
	ds_read2st64_b32 v[8:9], v87 offset0:6 offset1:7
	s_cmpk_gt_u32 s28, 0xbff
	s_waitcnt lgkmcnt(3)
	v_and_b32_e32 v11, 0x7fffffff, v3
	s_waitcnt lgkmcnt(2)
	v_and_b32_e32 v10, 0x7fffffff, v4
	v_xor_b32_e32 v12, -1, v3
	v_pk_add_f32 v[10:11], v[10:11], 0 neg_lo:[1,1] neg_hi:[1,1]
	v_cmp_gt_i32_e32 vcc, 0, v3
	v_xor_b32_e32 v13, -1, v4
	v_xor_b32_e32 v3, -1, v5
	s_waitcnt vmcnt(8)
	v_cndmask_b32_e32 v49, v11, v12, vcc
	v_cmp_gt_i32_e32 vcc, 0, v4
	v_and_b32_e32 v11, 0x7fffffff, v5
	s_waitcnt lgkmcnt(1)
	v_xor_b32_e32 v4, -1, v6
	v_cndmask_b32_e32 v47, v10, v13, vcc
	v_and_b32_e32 v10, 0x7fffffff, v6
	v_pk_add_f32 v[10:11], v[10:11], 0 neg_lo:[1,1] neg_hi:[1,1]
	v_cmp_gt_i32_e32 vcc, 0, v5
	v_and_b32_e32 v5, 0x7fffffff, v7
	s_waitcnt lgkmcnt(0)
	v_and_b32_e32 v15, 0x7fffffff, v9
	v_cndmask_b32_e32 v46, v11, v3, vcc
	v_cmp_gt_i32_e32 vcc, 0, v6
	v_xor_b32_e32 v3, -1, v7
	v_xor_b32_e32 v6, -1, v8
	v_cndmask_b32_e32 v44, v10, v4, vcc
	v_and_b32_e32 v4, 0x7fffffff, v8
	v_pk_add_f32 v[4:5], v[4:5], 0 neg_lo:[1,1] neg_hi:[1,1]
	v_cmp_gt_i32_e32 vcc, 0, v7
	s_nop 1
	v_cndmask_b32_e32 v43, v5, v3, vcc
	v_cmp_gt_i32_e32 vcc, 0, v8
	v_xor_b32_e32 v3, -1, v9
	s_nop 0
	v_cndmask_b32_e32 v41, v4, v6, vcc
	ds_read2st64_b32 v[4:5], v87 offset0:8 offset1:9
	ds_read2st64_b32 v[6:7], v87 offset0:10 offset1:11
	ds_read2st64_b32 v[10:11], v87 offset0:12 offset1:13
	ds_read2st64_b32 v[12:13], v87 offset0:14 offset1:15
	v_cmp_gt_i32_e32 vcc, 0, v9
	s_waitcnt lgkmcnt(3)
	v_and_b32_e32 v14, 0x7fffffff, v4
	v_pk_add_f32 v[14:15], v[14:15], 0 neg_lo:[1,1] neg_hi:[1,1]
	v_xor_b32_e32 v8, -1, v4
	v_cndmask_b32_e32 v48, v15, v3, vcc
	v_cmp_gt_i32_e32 vcc, 0, v4
	v_and_b32_e32 v9, 0x7fffffff, v5
	v_xor_b32_e32 v3, -1, v5
	v_cndmask_b32_e32 v45, v14, v8, vcc
	s_waitcnt lgkmcnt(2)
	v_and_b32_e32 v8, 0x7fffffff, v6
	v_pk_add_f32 v[8:9], v[8:9], 0 neg_lo:[1,1] neg_hi:[1,1]
	v_cmp_gt_i32_e32 vcc, 0, v5
	v_xor_b32_e32 v4, -1, v6
	v_and_b32_e32 v5, 0x7fffffff, v7
	v_cndmask_b32_e32 v42, v9, v3, vcc
	v_cmp_gt_i32_e32 vcc, 0, v6
	v_xor_b32_e32 v3, -1, v7
	s_waitcnt lgkmcnt(1)
	v_xor_b32_e32 v6, -1, v10
	v_cndmask_b32_e32 v40, v8, v4, vcc
	v_and_b32_e32 v4, 0x7fffffff, v10
	v_pk_add_f32 v[4:5], v[4:5], 0 neg_lo:[1,1] neg_hi:[1,1]
	v_cmp_gt_i32_e32 vcc, 0, v7
	s_waitcnt lgkmcnt(0)
	v_and_b32_e32 v15, 0x7fffffff, v13
	v_cndmask_b32_e32 v38, v5, v3, vcc
	v_cmp_gt_i32_e32 vcc, 0, v10
	v_and_b32_e32 v5, 0x7fffffff, v11
	v_xor_b32_e32 v3, -1, v11
	v_cndmask_b32_e32 v36, v4, v6, vcc
	v_and_b32_e32 v4, 0x7fffffff, v12
	v_pk_add_f32 v[4:5], v[4:5], 0 neg_lo:[1,1] neg_hi:[1,1]
	v_cmp_gt_i32_e32 vcc, 0, v11
	v_xor_b32_e32 v6, -1, v12
	s_nop 0
	v_cndmask_b32_e32 v35, v5, v3, vcc
	v_cmp_gt_i32_e32 vcc, 0, v12
	v_xor_b32_e32 v3, -1, v13
	s_nop 0
	v_cndmask_b32_e32 v33, v4, v6, vcc
	ds_read2st64_b32 v[4:5], v87 offset0:16 offset1:17
	ds_read2st64_b32 v[6:7], v87 offset0:18 offset1:19
	ds_read2st64_b32 v[8:9], v87 offset0:20 offset1:21
	ds_read2st64_b32 v[10:11], v87 offset0:22 offset1:23
	v_cmp_gt_i32_e32 vcc, 0, v13
	s_waitcnt lgkmcnt(3)
	v_and_b32_e32 v14, 0x7fffffff, v4
	v_pk_add_f32 v[14:15], v[14:15], 0 neg_lo:[1,1] neg_hi:[1,1]
	v_xor_b32_e32 v12, -1, v4
	v_cndmask_b32_e32 v39, v15, v3, vcc
	v_cmp_gt_i32_e32 vcc, 0, v4
	v_and_b32_e32 v13, 0x7fffffff, v5
	v_xor_b32_e32 v3, -1, v5
	v_cndmask_b32_e32 v37, v14, v12, vcc
	s_waitcnt lgkmcnt(2)
	v_and_b32_e32 v12, 0x7fffffff, v6
	v_pk_add_f32 v[12:13], v[12:13], 0 neg_lo:[1,1] neg_hi:[1,1]
	v_cmp_gt_i32_e32 vcc, 0, v5
	v_xor_b32_e32 v4, -1, v6
	v_and_b32_e32 v5, 0x7fffffff, v7
	v_cndmask_b32_e32 v34, v13, v3, vcc
	v_cmp_gt_i32_e32 vcc, 0, v6
	v_xor_b32_e32 v3, -1, v7
	s_waitcnt lgkmcnt(1)
	v_xor_b32_e32 v6, -1, v8
	v_cndmask_b32_e32 v32, v12, v4, vcc
	v_and_b32_e32 v4, 0x7fffffff, v8
	v_pk_add_f32 v[4:5], v[4:5], 0 neg_lo:[1,1] neg_hi:[1,1]
	v_cmp_gt_i32_e32 vcc, 0, v7
	s_waitcnt lgkmcnt(0)
	v_and_b32_e32 v15, 0x7fffffff, v11
	v_cndmask_b32_e32 v30, v5, v3, vcc
	v_cmp_gt_i32_e32 vcc, 0, v8
	v_and_b32_e32 v5, 0x7fffffff, v9
	v_xor_b32_e32 v3, -1, v9
	v_cndmask_b32_e32 v28, v4, v6, vcc
	v_and_b32_e32 v4, 0x7fffffff, v10
	v_pk_add_f32 v[4:5], v[4:5], 0 neg_lo:[1,1] neg_hi:[1,1]
	v_cmp_gt_i32_e32 vcc, 0, v9
	v_xor_b32_e32 v6, -1, v10
	s_nop 0
	v_cndmask_b32_e32 v25, v5, v3, vcc
	v_cmp_gt_i32_e32 vcc, 0, v10
	v_xor_b32_e32 v3, -1, v11
	s_nop 0
	v_cndmask_b32_e32 v23, v4, v6, vcc
	ds_read2st64_b32 v[4:5], v87 offset0:24 offset1:25
	ds_read2st64_b32 v[6:7], v87 offset0:26 offset1:27
	ds_read2st64_b32 v[8:9], v87 offset0:28 offset1:29
	ds_read2st64_b32 v[12:13], v87 offset0:30 offset1:31
	v_cmp_gt_i32_e32 vcc, 0, v11
	s_waitcnt lgkmcnt(3)
	v_and_b32_e32 v14, 0x7fffffff, v4
	v_pk_add_f32 v[14:15], v[14:15], 0 neg_lo:[1,1] neg_hi:[1,1]
	v_xor_b32_e32 v10, -1, v4
	v_cndmask_b32_e32 v31, v15, v3, vcc
	v_cmp_gt_i32_e32 vcc, 0, v4
	v_and_b32_e32 v11, 0x7fffffff, v5
	v_xor_b32_e32 v3, -1, v5
	v_cndmask_b32_e32 v29, v14, v10, vcc
	s_waitcnt lgkmcnt(2)
	v_and_b32_e32 v10, 0x7fffffff, v6
	v_pk_add_f32 v[10:11], v[10:11], 0 neg_lo:[1,1] neg_hi:[1,1]
	v_cmp_gt_i32_e32 vcc, 0, v5
	v_xor_b32_e32 v4, -1, v6
	v_and_b32_e32 v5, 0x7fffffff, v7
	v_cndmask_b32_e32 v24, v11, v3, vcc
	v_cmp_gt_i32_e32 vcc, 0, v6
	v_xor_b32_e32 v3, -1, v7
	s_waitcnt lgkmcnt(1)
; DI unsigned fkey(float f) { unsigned u = __float_as_uint(f); return (u & 0x80000000u) ? ~u : (u | 0x80000000u); }
; template <int NR>
; DI u64 select_wave(float* scw, int nreg, int lane) {
;     ...
; #pragma unroll
;   for (int r = 0; r < NR; ++r) {
;     const unsigned k = fkey(scw[64 * r + lane]);
;     const bool ok = r < nreg;
;     key[r] = ok ? k : 0u;
;     kmin = min(kmin, ok ? k : 0xffffffffu); kmax = max(kmax, key[r]);
;   }
	v_xor_b32_e32 v6, -1, v8
	v_cndmask_b32_e32 v22, v10, v4, vcc
	v_and_b32_e32 v4, 0x7fffffff, v8
	v_pk_add_f32 v[4:5], v[4:5], 0 neg_lo:[1,1] neg_hi:[1,1]
	v_cmp_gt_i32_e32 vcc, 0, v7
	s_nop 1
	v_cndmask_b32_e32 v21, v5, v3, vcc
	v_cmp_gt_i32_e32 vcc, 0, v8
	v_and_b32_e32 v5, 0x7fffffff, v9
	v_xor_b32_e32 v3, -1, v9
	v_cndmask_b32_e32 v19, v4, v6, vcc
	ds_read2st64_b32 v[6:7], v87 offset0:32 offset1:33
	s_waitcnt lgkmcnt(1)
	v_and_b32_e32 v4, 0x7fffffff, v12
	v_pk_add_f32 v[4:5], v[4:5], 0 neg_lo:[1,1] neg_hi:[1,1]
	v_cmp_gt_i32_e32 vcc, 0, v9
	v_xor_b32_e32 v8, -1, v12
	s_nop 0
	v_cndmask_b32_e32 v20, v5, v3, vcc
	v_cmp_gt_i32_e32 vcc, 0, v12
	v_and_b32_e32 v5, 0x7fffffff, v13
	v_xor_b32_e32 v3, -1, v13
	v_cndmask_b32_e32 v18, v4, v8, vcc
	s_waitcnt lgkmcnt(0)
	v_and_b32_e32 v4, 0x7fffffff, v6
	v_pk_add_f32 v[4:5], v[4:5], 0 neg_lo:[1,1] neg_hi:[1,1]
	v_cmp_gt_i32_e32 vcc, 0, v13
	v_xor_b32_e32 v8, -1, v6
	s_nop 0
	v_cndmask_b32_e32 v17, v5, v3, vcc
	v_cmp_gt_i32_e32 vcc, 0, v6
	v_and_b32_e32 v5, 0x7fffffff, v2
	v_xor_b32_e32 v3, -1, v2
	v_cndmask_b32_e32 v16, v4, v8, vcc
	v_and_b32_e32 v4, 0x7fffffff, v7
	v_pk_add_f32 v[4:5], v[4:5], 0 neg_lo:[1,1] neg_hi:[1,1]
	v_cmp_gt_i32_e32 vcc, 0, v2
	v_xor_b32_e32 v6, -1, v7
	s_nop 0
	v_cndmask_b32_e32 v50, v5, v3, vcc
	v_min3_u32 v2, v50, v49, v47
	v_max3_u32 v3, v50, v49, v47
	v_min3_u32 v2, v2, v46, v44
	v_max3_u32 v3, v3, v46, v44
	v_min3_u32 v2, v2, v43, v41
	v_max3_u32 v3, v3, v43, v41
	v_min3_u32 v2, v2, v48, v45
	v_max3_u32 v3, v3, v48, v45
	v_min3_u32 v2, v2, v42, v40
	v_max3_u32 v3, v3, v42, v40
	v_min3_u32 v2, v2, v38, v36
	v_max3_u32 v3, v3, v38, v36
	v_min3_u32 v2, v2, v35, v33
	v_max3_u32 v3, v3, v35, v33
	v_min3_u32 v2, v2, v39, v37
	v_max3_u32 v3, v3, v39, v37
	v_min3_u32 v2, v2, v34, v32
	v_max3_u32 v3, v3, v34, v32
	v_min3_u32 v2, v2, v30, v28
	v_max3_u32 v3, v3, v30, v28
	v_min3_u32 v2, v2, v25, v23
	v_max3_u32 v3, v3, v25, v23
	v_min3_u32 v2, v2, v31, v29
	v_max3_u32 v3, v3, v31, v29
	v_min3_u32 v2, v2, v24, v22
	v_max3_u32 v3, v3, v24, v22
	v_min3_u32 v2, v2, v21, v19
	v_max3_u32 v3, v3, v21, v19
	v_cmp_gt_i32_e32 vcc, 0, v7
	v_min3_u32 v2, v2, v20, v18
	v_max3_u32 v3, v3, v20, v18
	v_cndmask_b32_e32 v51, v4, v6, vcc
	v_min3_u32 v52, v2, v17, v16
	v_max3_u32 v53, v3, v17, v16
	s_cbranch_scc0 .LBB0_368
	ds_read2st64_b32 v[2:3], v87 offset0:34 offset1:35
	v_max_u32_e32 v8, v53, v51
	s_cmpk_gt_u32 s28, 0xc3f
	s_mov_b32 s5, 0
	s_mov_b32 s44, 0
	s_waitcnt lgkmcnt(0)
	v_not_b32_e32 v4, v2
	v_or_b32_e32 v5, 0x80000000, v2
	v_cmp_gt_i32_e32 vcc, 0, v2
	v_and_b32_e32 v7, 0x7fffffff, v3
	v_xor_b32_e32 v2, -1, v3
	v_cndmask_b32_e32 v54, v5, v4, vcc
	ds_read2st64_b32 v[4:5], v87 offset0:36 offset1:37
	v_cmp_gt_i32_e64 s[0:1], 0, v3
	v_min3_u32 v9, v52, v51, v54
	s_mov_b32 s6, s4
	s_waitcnt lgkmcnt(0)
	v_and_b32_e32 v6, 0x7fffffff, v4
	v_xor_b32_e32 v10, -1, v4
	v_pk_add_f32 v[6:7], v[6:7], 0 neg_lo:[1,1] neg_hi:[1,1]
	v_cmp_gt_i32_e32 vcc, 0, v4
	v_cndmask_b32_e64 v3, v7, v2, s[0:1]
	v_xor_b32_e32 v4, -1, v5
	v_cndmask_b32_e32 v2, v6, v10, vcc
	ds_read2st64_b32 v[6:7], v87 offset0:38 offset1:39
	v_max3_u32 v10, v8, v54, v3
	v_min3_u32 v11, v9, v3, v2
	v_and_b32_e32 v9, 0x7fffffff, v5
	v_cmp_gt_i32_e64 s[0:1], 0, v5
	s_waitcnt lgkmcnt(0)
	v_and_b32_e32 v8, 0x7fffffff, v6
	v_xor_b32_e32 v12, -1, v6
	v_pk_add_f32 v[8:9], v[8:9], 0 neg_lo:[1,1] neg_hi:[1,1]
	v_cmp_gt_i32_e32 vcc, 0, v6
	v_cndmask_b32_e64 v5, v9, v4, s[0:1]
	v_max3_u32 v6, v10, v2, v5
	v_cndmask_b32_e32 v4, v8, v12, vcc
	v_min3_u32 v12, v11, v5, v4
	ds_read2st64_b32 v[10:11], v87 offset0:40 offset1:41
	v_and_b32_e32 v9, 0x7fffffff, v7
	v_xor_b32_e32 v13, -1, v7
	v_cmp_gt_i32_e64 s[0:1], 0, v7
	s_waitcnt lgkmcnt(0)
	v_and_b32_e32 v8, 0x7fffffff, v10
	v_xor_b32_e32 v14, -1, v10
	v_pk_add_f32 v[8:9], v[8:9], 0 neg_lo:[1,1] neg_hi:[1,1]
	v_cmp_gt_i32_e32 vcc, 0, v10
	v_cndmask_b32_e64 v9, v9, v13, s[0:1]
	v_max3_u32 v10, v6, v4, v9
	v_cndmask_b32_e32 v8, v8, v14, vcc
	v_min3_u32 v14, v12, v9, v8
	ds_read2st64_b32 v[12:13], v87 offset0:42 offset1:43
	v_and_b32_e32 v7, 0x7fffffff, v11
	v_xor_b32_e32 v15, -1, v11
	v_cmp_gt_i32_e64 s[0:1], 0, v11
	s_waitcnt lgkmcnt(0)
	v_and_b32_e32 v6, 0x7fffffff, v12
	v_xor_b32_e32 v26, -1, v12
	v_pk_add_f32 v[6:7], v[6:7], 0 neg_lo:[1,1] neg_hi:[1,1]
	v_cmp_gt_i32_e32 vcc, 0, v12
	v_cndmask_b32_e64 v7, v7, v15, s[0:1]
	v_max3_u32 v12, v10, v8, v7
	v_cndmask_b32_e32 v6, v6, v26, vcc
	v_min3_u32 v26, v14, v7, v6
	ds_read2st64_b32 v[14:15], v87 offset0:44 offset1:45
	v_and_b32_e32 v11, 0x7fffffff, v13
	v_xor_b32_e32 v27, -1, v13
	v_cmp_gt_i32_e64 s[0:1], 0, v13
	s_waitcnt lgkmcnt(0)
	v_and_b32_e32 v10, 0x7fffffff, v14
	v_xor_b32_e32 v55, -1, v14
	v_pk_add_f32 v[10:11], v[10:11], 0 neg_lo:[1,1] neg_hi:[1,1]
	v_cmp_gt_i32_e32 vcc, 0, v14
	v_cndmask_b32_e64 v11, v11, v27, s[0:1]
	v_max3_u32 v14, v12, v6, v11
	v_cndmask_b32_e32 v10, v10, v55, vcc
	v_min3_u32 v55, v26, v11, v10
	ds_read2st64_b32 v[26:27], v87 offset0:46 offset1:47
	v_and_b32_e32 v13, 0x7fffffff, v15
	v_xor_b32_e32 v56, -1, v15
	v_cmp_gt_i32_e64 s[0:1], 0, v15
	s_waitcnt lgkmcnt(0)
	v_and_b32_e32 v12, 0x7fffffff, v26
	v_xor_b32_e32 v57, -1, v26
	v_pk_add_f32 v[12:13], v[12:13], 0 neg_lo:[1,1] neg_hi:[1,1]
	v_cmp_gt_i32_e32 vcc, 0, v26
	v_cndmask_b32_e64 v13, v13, v56, s[0:1]
	v_max3_u32 v26, v14, v10, v13
	v_cndmask_b32_e32 v12, v12, v57, vcc
	ds_read2st64_b32 v[56:57], v87 offset0:48 offset1:49
	v_and_b32_e32 v15, 0x7fffffff, v27
	v_xor_b32_e32 v58, -1, v27
	v_cmp_gt_i32_e64 s[0:1], 0, v27
	v_min3_u32 v55, v55, v13, v12
	s_waitcnt lgkmcnt(0)
; DI unsigned fkey(float f) { unsigned u = __float_as_uint(f); return (u & 0x80000000u) ? ~u : (u | 0x80000000u); }
; template <int NR>
; DI u64 select_wave(float* scw, int nreg, int lane) {
;     ...
; #pragma unroll
;   for (int r = 0; r < NR; ++r) {
;     const unsigned k = fkey(scw[64 * r + lane]);
;     const bool ok = r < nreg;
;     key[r] = ok ? k : 0u;
;     kmin = min(kmin, ok ? k : 0xffffffffu); kmax = max(kmax, key[r]);
;   }
; #pragma unroll
;   for (int o = 1; o < 64; o <<= 1) { kmin = min(kmin, (unsigned)__shfl_xor((int)kmin, o)); kmax = max(kmax, (unsigned)__shfl_xor((int)kmax, o)); }
;   unsigned lo = __builtin_amdgcn_readfirstlane(kmin), hi = __builtin_amdgcn_readfirstlane(kmax);
	v_and_b32_e32 v14, 0x7fffffff, v56
	v_xor_b32_e32 v59, -1, v56
	v_pk_add_f32 v[14:15], v[14:15], 0 neg_lo:[1,1] neg_hi:[1,1]
	v_cmp_gt_i32_e32 vcc, 0, v56
	v_cndmask_b32_e64 v15, v15, v58, s[0:1]
	v_or_b32_e32 v56, 0x80000000, v57
	v_cndmask_b32_e32 v14, v14, v59, vcc
	v_min3_u32 v27, v55, v15, v14
	v_not_b32_e32 v55, v57
	v_cmp_gt_i32_e32 vcc, 0, v57
	v_max3_u32 v26, v26, v12, v15
	s_mov_b64 s[0:1], 0
	v_cndmask_b32_e32 v55, v56, v55, vcc
	s_cselect_b64 vcc, -1, 0
	v_cndmask_b32_e32 v56, 0, v55, vcc
	v_min_u32_e32 v55, v27, v55
	v_cndmask_b32_e32 v55, v27, v55, vcc
	v_max3_u32 v58, v26, v14, v56
	ds_read2st64_b32 v[26:27], v87 offset0:50 offset1:51
	s_cmpk_gt_u32 s28, 0xc7f
	s_waitcnt lgkmcnt(0)
	v_not_b32_e32 v57, v26
	v_or_b32_e32 v59, 0x80000000, v26
	v_cmp_gt_i32_e32 vcc, 0, v26
	s_nop 1
	v_cndmask_b32_e32 v26, v59, v57, vcc
	s_cselect_b64 vcc, -1, 0
	v_cndmask_b32_e32 v57, 0, v26, vcc
	v_min_u32_e32 v26, v55, v26
	v_cndmask_b32_e32 v26, v55, v26, vcc
	v_not_b32_e32 v55, v27
	v_or_b32_e32 v59, 0x80000000, v27
	v_cmp_gt_i32_e32 vcc, 0, v27
	s_cmpk_gt_u32 s28, 0xcbf
	s_nop 0
	v_cndmask_b32_e32 v27, v59, v55, vcc
	s_cselect_b64 vcc, -1, 0
	v_cndmask_b32_e32 v55, 0, v27, vcc
	v_min_u32_e32 v27, v26, v27
	v_cndmask_b32_e32 v60, v26, v27, vcc
	ds_read2st64_b32 v[26:27], v87 offset0:52 offset1:53
	v_max3_u32 v61, v58, v57, v55
	s_cmpk_gt_u32 s28, 0xcff
	s_waitcnt lgkmcnt(0)
	v_not_b32_e32 v58, v26
	v_or_b32_e32 v59, 0x80000000, v26
	v_cmp_gt_i32_e32 vcc, 0, v26
	s_nop 1
	v_cndmask_b32_e32 v26, v59, v58, vcc
	s_cselect_b64 vcc, -1, 0
	v_cndmask_b32_e32 v59, 0, v26, vcc
	v_min_u32_e32 v26, v60, v26
	v_cndmask_b32_e32 v26, v60, v26, vcc
	v_not_b32_e32 v58, v27
	v_or_b32_e32 v60, 0x80000000, v27
	v_cmp_gt_i32_e32 vcc, 0, v27
	s_cmpk_gt_u32 s28, 0xd3f
	s_nop 0
	v_cndmask_b32_e32 v27, v60, v58, vcc
	s_cselect_b64 vcc, -1, 0
	v_cndmask_b32_e32 v58, 0, v27, vcc
	v_min_u32_e32 v27, v26, v27
	v_cndmask_b32_e32 v60, v26, v27, vcc
	ds_read2st64_b32 v[26:27], v87 offset0:54 offset1:55
	v_max3_u32 v62, v61, v59, v58
	s_cmpk_gt_u32 s28, 0xd7f
	s_waitcnt lgkmcnt(0)
	v_not_b32_e32 v61, v26
	v_or_b32_e32 v63, 0x80000000, v26
	v_cmp_gt_i32_e32 vcc, 0, v26
	s_nop 1
	v_cndmask_b32_e32 v26, v63, v61, vcc
	s_cselect_b64 vcc, -1, 0
	v_cndmask_b32_e32 v61, 0, v26, vcc
	v_min_u32_e32 v26, v60, v26
	v_cndmask_b32_e32 v26, v60, v26, vcc
	v_not_b32_e32 v60, v27
	v_or_b32_e32 v63, 0x80000000, v27
	v_cmp_gt_i32_e32 vcc, 0, v27
	s_cmpk_gt_u32 s28, 0xdbf
	s_nop 0
	v_cndmask_b32_e32 v27, v63, v60, vcc
	s_cselect_b64 vcc, -1, 0
	v_cndmask_b32_e32 v60, 0, v27, vcc
	v_min_u32_e32 v27, v26, v27
	v_cndmask_b32_e32 v63, v26, v27, vcc
	ds_read2st64_b32 v[26:27], v87 offset0:56 offset1:57
	v_max3_u32 v65, v62, v61, v60
	s_cmpk_gt_u32 s28, 0xdff
	s_waitcnt lgkmcnt(0)
	v_not_b32_e32 v62, v26
	v_or_b32_e32 v64, 0x80000000, v26
	v_cmp_gt_i32_e32 vcc, 0, v26
	s_nop 1
	v_cndmask_b32_e32 v26, v64, v62, vcc
	s_cselect_b64 vcc, -1, 0
	v_cndmask_b32_e32 v64, 0, v26, vcc
	v_min_u32_e32 v26, v63, v26
	v_cndmask_b32_e32 v26, v63, v26, vcc
	v_not_b32_e32 v62, v27
	v_or_b32_e32 v63, 0x80000000, v27
	v_cmp_gt_i32_e32 vcc, 0, v27
	s_cmpk_gt_u32 s28, 0xe3f
	s_nop 0
	v_cndmask_b32_e32 v27, v63, v62, vcc
	s_cselect_b64 vcc, -1, 0
	v_cndmask_b32_e32 v62, 0, v27, vcc
	v_min_u32_e32 v27, v26, v27
	v_cndmask_b32_e32 v63, v26, v27, vcc
	ds_read2st64_b32 v[26:27], v87 offset0:58 offset1:59
	v_max3_u32 v66, v65, v64, v62
	s_cmpk_gt_u32 s28, 0xe7f
	s_waitcnt lgkmcnt(0)
	v_not_b32_e32 v65, v26
	v_or_b32_e32 v67, 0x80000000, v26
	v_cmp_gt_i32_e32 vcc, 0, v26
	s_nop 1
	v_cndmask_b32_e32 v26, v67, v65, vcc
	s_cselect_b64 vcc, -1, 0
	v_cndmask_b32_e32 v65, 0, v26, vcc
	v_min_u32_e32 v26, v63, v26
	v_cndmask_b32_e32 v26, v63, v26, vcc
	v_not_b32_e32 v63, v27
	v_or_b32_e32 v67, 0x80000000, v27
	v_cmp_gt_i32_e32 vcc, 0, v27
	s_cmpk_gt_u32 s28, 0xebf
	s_nop 0
	v_cndmask_b32_e32 v27, v67, v63, vcc
	s_cselect_b64 vcc, -1, 0
	v_cndmask_b32_e32 v63, 0, v27, vcc
	v_min_u32_e32 v27, v26, v27
	v_cndmask_b32_e32 v68, v26, v27, vcc
	ds_read2st64_b32 v[26:27], v87 offset0:60 offset1:61
	v_max3_u32 v69, v66, v65, v63
	s_cmpk_gt_u32 s28, 0xeff
	s_waitcnt lgkmcnt(0)
	v_not_b32_e32 v66, v26
	v_or_b32_e32 v67, 0x80000000, v26
	v_cmp_gt_i32_e32 vcc, 0, v26
	s_nop 1
	v_cndmask_b32_e32 v26, v67, v66, vcc
	s_cselect_b64 vcc, -1, 0
	v_cndmask_b32_e32 v67, 0, v26, vcc
	v_min_u32_e32 v26, v68, v26
	v_cndmask_b32_e32 v26, v68, v26, vcc
	v_not_b32_e32 v66, v27
	v_or_b32_e32 v68, 0x80000000, v27
	v_cmp_gt_i32_e32 vcc, 0, v27
	s_cmpk_gt_u32 s28, 0xf3f
	s_nop 0
	v_cndmask_b32_e32 v27, v68, v66, vcc
	s_cselect_b64 vcc, -1, 0
	v_cndmask_b32_e32 v66, 0, v27, vcc
	v_min_u32_e32 v27, v26, v27
	v_cndmask_b32_e32 v68, v26, v27, vcc
	ds_read2st64_b32 v[26:27], v87 offset0:62 offset1:63
	v_max3_u32 v70, v69, v67, v66
	s_cmpk_gt_u32 s28, 0xf7f
	s_waitcnt lgkmcnt(0)
	v_not_b32_e32 v69, v26
	v_or_b32_e32 v71, 0x80000000, v26
	v_cmp_gt_i32_e32 vcc, 0, v26
	s_nop 1
	v_cndmask_b32_e32 v26, v71, v69, vcc
	s_cselect_b64 vcc, -1, 0
	v_cndmask_b32_e32 v69, 0, v26, vcc
	v_min_u32_e32 v26, v68, v26
	v_cndmask_b32_e32 v26, v68, v26, vcc
	v_not_b32_e32 v68, v27
	v_or_b32_e32 v71, 0x80000000, v27
	v_cmp_gt_i32_e32 vcc, 0, v27
	s_cmpk_gt_u32 s28, 0xfbf
	s_nop 0
	v_cndmask_b32_e32 v27, v71, v68, vcc
	s_cselect_b64 vcc, -1, 0
	v_cndmask_b32_e32 v68, 0, v27, vcc
	v_min_u32_e32 v27, v26, v27
	v_cndmask_b32_e32 v26, v26, v27, vcc
	v_max3_u32 v27, v70, v69, v68
	s_waitcnt lgkmcnt(0)
	s_nop 1
	v_min_u32_dpp v26, v26, v26 quad_perm:[1,0,3,2] row_mask:0xf bank_mask:0xf
	v_max_u32_dpp v27, v27, v27 quad_perm:[1,0,3,2] row_mask:0xf bank_mask:0xf
	s_nop 0
	v_min_u32_dpp v26, v26, v26 quad_perm:[2,3,0,1] row_mask:0xf bank_mask:0xf
	v_max_u32_dpp v27, v27, v27 quad_perm:[2,3,0,1] row_mask:0xf bank_mask:0xf
	s_nop 0
	v_min_u32_dpp v26, v26, v26 row_half_mirror row_mask:0xf bank_mask:0xf
	v_max_u32_dpp v27, v27, v27 row_half_mirror row_mask:0xf bank_mask:0xf
	s_nop 0
	v_min_u32_dpp v26, v26, v26 row_mirror row_mask:0xf bank_mask:0xf
	v_max_u32_dpp v27, v27, v27 row_mirror row_mask:0xf bank_mask:0xf
	s_nop 0
	v_min_u32_dpp v26, v26, v26 row_bcast:15 row_mask:0xa bank_mask:0xf
	v_max_u32_dpp v27, v27, v27 row_bcast:15 row_mask:0xa bank_mask:0xf
	s_nop 0
	v_min_u32_dpp v26, v26, v26 row_bcast:31 row_mask:0xc bank_mask:0xf
	v_max_u32_dpp v27, v27, v27 row_bcast:31 row_mask:0xc bank_mask:0xf
	s_nop 0
	v_readlane_b32 s81, v26, 63
	v_readlane_b32 s80, v27, 63

; DI unsigned fkey(float f) { unsigned u = __float_as_uint(f); return (u & 0x80000000u) ? ~u : (u | 0x80000000u); }
; template <int NR>
; DI u64 select_wave(float* scw, int nreg, int lane) {
;     ...
; #pragma unroll
;   for (int r = 0; r < NR; ++r) {
;     const unsigned k = fkey(scw[64 * r + lane]);
;     const bool ok = r < nreg;
;     key[r] = ok ? k : 0u;
;     kmin = min(kmin, ok ? k : 0xffffffffu); kmax = max(kmax, key[r]);
;   }
; #pragma unroll
;   for (int o = 1; o < 64; o <<= 1) { kmin = min(kmin, (unsigned)__shfl_xor((int)kmin, o)); kmax = max(kmax, (unsigned)__shfl_xor((int)kmax, o)); }
;   unsigned lo = __builtin_amdgcn_readfirstlane(kmin), hi = __builtin_amdgcn_readfirstlane(kmax);
.LBB0_368:
	s_and_b64 vcc, exec, s[0:1]
	s_cbranch_vccz .LBB0_495
	ds_read2st64_b32 v[4:5], v87 offset0:34 offset1:35
	s_cmpk_gt_u32 s28, 0x83f
	s_cselect_b64 vcc, -1, 0
	v_min_u32_e32 v3, v52, v51
	v_cndmask_b32_e32 v2, 0, v51, vcc
	v_cndmask_b32_e32 v3, v52, v3, vcc
	s_waitcnt lgkmcnt(0)
	v_not_b32_e32 v7, v4
	v_or_b32_e32 v8, 0x80000000, v4
	v_cmp_gt_i32_e32 vcc, 0, v4
	s_cmpk_gt_u32 s28, 0x87f
	v_max_u32_e32 v6, v53, v2
	v_cndmask_b32_e32 v7, v8, v7, vcc
	s_cselect_b64 vcc, -1, 0
	v_cndmask_b32_e32 v4, 0, v7, vcc
	v_min_u32_e32 v7, v3, v7
	v_cndmask_b32_e32 v7, v3, v7, vcc
	v_not_b32_e32 v3, v5
	v_or_b32_e32 v8, 0x80000000, v5
	v_cmp_gt_i32_e32 vcc, 0, v5
	s_cmpk_gt_u32 s28, 0x8bf
	s_mov_b32 s5, 0
	v_cndmask_b32_e32 v5, v8, v3, vcc
	s_cselect_b64 vcc, -1, 0
	v_cndmask_b32_e32 v3, 0, v5, vcc
	v_min_u32_e32 v5, v7, v5
	v_cndmask_b32_e32 v5, v7, v5, vcc
	v_max3_u32 v8, v6, v4, v3
	ds_read2st64_b32 v[6:7], v87 offset0:36 offset1:37
	s_cmpk_gt_u32 s28, 0x8ff
	s_mov_b64 s[0:1], 0
	s_mov_b32 s44, 0
	s_mov_b32 s6, s4
	s_waitcnt lgkmcnt(0)
	v_not_b32_e32 v9, v6
	v_or_b32_e32 v10, 0x80000000, v6
	v_cmp_gt_i32_e32 vcc, 0, v6
	s_nop 1
	v_cndmask_b32_e32 v9, v10, v9, vcc
	s_cselect_b64 vcc, -1, 0
	v_cndmask_b32_e32 v6, 0, v9, vcc
	v_min_u32_e32 v9, v5, v9
	v_cndmask_b32_e32 v9, v5, v9, vcc
	v_not_b32_e32 v5, v7
	v_or_b32_e32 v10, 0x80000000, v7
	v_cmp_gt_i32_e32 vcc, 0, v7
	s_cmpk_gt_u32 s28, 0x93f
	s_nop 0
	v_cndmask_b32_e32 v7, v10, v5, vcc
	s_cselect_b64 vcc, -1, 0
	v_cndmask_b32_e32 v5, 0, v7, vcc
	v_min_u32_e32 v7, v9, v7
	v_cndmask_b32_e32 v7, v9, v7, vcc
	v_max3_u32 v10, v8, v6, v5
	ds_read2st64_b32 v[8:9], v87 offset0:38 offset1:39
	s_cmpk_gt_u32 s28, 0x97f
	s_waitcnt lgkmcnt(0)
	v_not_b32_e32 v11, v8
	v_or_b32_e32 v12, 0x80000000, v8
	v_cmp_gt_i32_e32 vcc, 0, v8
	s_nop 1
	v_cndmask_b32_e32 v11, v12, v11, vcc
	s_cselect_b64 vcc, -1, 0
	v_cndmask_b32_e32 v8, 0, v11, vcc
	v_min_u32_e32 v11, v7, v11
	v_cndmask_b32_e32 v11, v7, v11, vcc
	v_not_b32_e32 v7, v9
	v_or_b32_e32 v12, 0x80000000, v9
	v_cmp_gt_i32_e32 vcc, 0, v9
	s_cmpk_gt_u32 s28, 0x9bf
	s_nop 0
	v_cndmask_b32_e32 v9, v12, v7, vcc
	ds_read2st64_b32 v[12:13], v87 offset0:40 offset1:41
	s_cselect_b64 vcc, -1, 0
	v_cndmask_b32_e32 v7, 0, v9, vcc
	v_min_u32_e32 v9, v11, v9
	v_cndmask_b32_e32 v9, v11, v9, vcc
	s_waitcnt lgkmcnt(0)
	v_not_b32_e32 v11, v12
	v_or_b32_e32 v14, 0x80000000, v12
	v_cmp_gt_i32_e32 vcc, 0, v12
	s_cmpk_gt_u32 s28, 0x9ff
	v_max3_u32 v10, v10, v8, v7
	v_cndmask_b32_e32 v12, v14, v11, vcc
	s_cselect_b64 vcc, -1, 0
	v_cndmask_b32_e32 v11, 0, v12, vcc
	v_min_u32_e32 v12, v9, v12
	v_cndmask_b32_e32 v12, v9, v12, vcc
	v_not_b32_e32 v9, v13
	v_or_b32_e32 v14, 0x80000000, v13
	v_cmp_gt_i32_e32 vcc, 0, v13
	s_cmpk_gt_u32 s28, 0xa3f
	s_nop 0
	v_cndmask_b32_e32 v13, v14, v9, vcc
	s_cselect_b64 vcc, -1, 0
	v_cndmask_b32_e32 v9, 0, v13, vcc
	v_min_u32_e32 v13, v12, v13
	v_cndmask_b32_e32 v14, v12, v13, vcc
	ds_read2st64_b32 v[12:13], v87 offset0:42 offset1:43
	v_max3_u32 v15, v10, v11, v9
	s_cmpk_gt_u32 s28, 0xa7f
	s_waitcnt lgkmcnt(0)
	v_not_b32_e32 v10, v12
	v_or_b32_e32 v26, 0x80000000, v12
	v_cmp_gt_i32_e32 vcc, 0, v12
	s_nop 1
	v_cndmask_b32_e32 v10, v26, v10, vcc
	s_cselect_b64 vcc, -1, 0
	v_cndmask_b32_e32 v12, 0, v10, vcc
	v_min_u32_e32 v10, v14, v10
	v_cndmask_b32_e32 v14, v14, v10, vcc
	v_not_b32_e32 v10, v13
	v_or_b32_e32 v26, 0x80000000, v13
	v_cmp_gt_i32_e32 vcc, 0, v13
	s_cmpk_gt_u32 s28, 0xabf
	s_nop 0
	v_cndmask_b32_e32 v13, v26, v10, vcc
	s_cselect_b64 vcc, -1, 0
	v_cndmask_b32_e32 v10, 0, v13, vcc
	v_min_u32_e32 v13, v14, v13
	v_cndmask_b32_e32 v13, v14, v13, vcc
	v_max3_u32 v26, v15, v12, v10
	ds_read2st64_b32 v[14:15], v87 offset0:44 offset1:45
	s_cmpk_gt_u32 s28, 0xaff
	s_waitcnt lgkmcnt(0)
	v_not_b32_e32 v27, v14
	v_or_b32_e32 v51, 0x80000000, v14
	v_cmp_gt_i32_e32 vcc, 0, v14
	s_nop 1
	v_cndmask_b32_e32 v27, v51, v27, vcc
	s_cselect_b64 vcc, -1, 0
	v_cndmask_b32_e32 v14, 0, v27, vcc
	v_min_u32_e32 v27, v13, v27
	v_cndmask_b32_e32 v27, v13, v27, vcc
	v_not_b32_e32 v13, v15
	v_or_b32_e32 v51, 0x80000000, v15
	v_cmp_gt_i32_e32 vcc, 0, v15
	s_cmpk_gt_u32 s28, 0xb3f
	s_nop 0
	v_cndmask_b32_e32 v15, v51, v13, vcc
	s_cselect_b64 vcc, -1, 0
	v_cndmask_b32_e32 v13, 0, v15, vcc
	v_min_u32_e32 v15, v27, v15
	v_cndmask_b32_e32 v15, v27, v15, vcc
	v_max3_u32 v52, v26, v14, v13
	ds_read2st64_b32 v[26:27], v87 offset0:46 offset1:47
	s_cmpk_gt_u32 s28, 0xb7f
	s_waitcnt lgkmcnt(0)
	v_not_b32_e32 v51, v26
	v_or_b32_e32 v53, 0x80000000, v26
	v_cmp_gt_i32_e32 vcc, 0, v26
	s_nop 1
	v_cndmask_b32_e32 v26, v53, v51, vcc
	s_cselect_b64 vcc, -1, 0
	v_cndmask_b32_e32 v51, 0, v26, vcc
	v_min_u32_e32 v26, v15, v26
	v_cndmask_b32_e32 v26, v15, v26, vcc
	v_not_b32_e32 v15, v27
	v_or_b32_e32 v53, 0x80000000, v27
	v_cmp_gt_i32_e32 vcc, 0, v27
	s_cmpk_gt_u32 s28, 0xbbf
	s_nop 0
	v_cndmask_b32_e32 v27, v53, v15, vcc
	s_cselect_b64 vcc, -1, 0
	v_cndmask_b32_e32 v15, 0, v27, vcc
	v_min_u32_e32 v27, v26, v27
	v_cndmask_b32_e32 v26, v26, v27, vcc
	v_max3_u32 v27, v52, v51, v15
	s_waitcnt lgkmcnt(0)
	s_nop 1
	v_min_u32_dpp v26, v26, v26 quad_perm:[1,0,3,2] row_mask:0xf bank_mask:0xf
	v_max_u32_dpp v27, v27, v27 quad_perm:[1,0,3,2] row_mask:0xf bank_mask:0xf
	s_nop 0
	v_min_u32_dpp v26, v26, v26 quad_perm:[2,3,0,1] row_mask:0xf bank_mask:0xf
	v_max_u32_dpp v27, v27, v27 quad_perm:[2,3,0,1] row_mask:0xf bank_mask:0xf
	s_nop 0
	v_min_u32_dpp v26, v26, v26 row_half_mirror row_mask:0xf bank_mask:0xf
	v_max_u32_dpp v27, v27, v27 row_half_mirror row_mask:0xf bank_mask:0xf
	s_nop 0
	v_min_u32_dpp v26, v26, v26 row_mirror row_mask:0xf bank_mask:0xf
	v_max_u32_dpp v27, v27, v27 row_mirror row_mask:0xf bank_mask:0xf
	s_nop 0
	v_min_u32_dpp v26, v26, v26 row_bcast:15 row_mask:0xa bank_mask:0xf
	v_max_u32_dpp v27, v27, v27 row_bcast:15 row_mask:0xa bank_mask:0xf
	s_nop 0
	v_min_u32_dpp v26, v26, v26 row_bcast:31 row_mask:0xc bank_mask:0xf
	v_max_u32_dpp v27, v27, v27 row_bcast:31 row_mask:0xc bank_mask:0xf
	s_nop 0
	v_readlane_b32 s79, v26, 63
	v_readlane_b32 s78, v27, 63

; DI unsigned fkey(float f) { unsigned u = __float_as_uint(f); return (u & 0x80000000u) ? ~u : (u | 0x80000000u); }
; template <int NR>
; DI u64 select_wave(float* scw, int nreg, int lane) {
;     ...
; #pragma unroll
;   for (int r = 0; r < NR; ++r) {
;     const unsigned k = fkey(scw[64 * r + lane]);
;     const bool ok = r < nreg;
;     key[r] = ok ? k : 0u;
;     kmin = min(kmin, ok ? k : 0xffffffffu); kmax = max(kmax, key[r]);
;   }
.LBB0_496:
	s_andn2_b64 vcc, exec, s[0:1]
	s_cbranch_vccnz .LBB0_590
	ds_read2st64_b32 v[2:3], v87 offset1:1
	s_cmpk_gt_u32 s28, 0x63f
	s_mov_b32 s5, 0
	s_mov_b32 s44, 0
	s_mov_b32 s6, s4
	s_waitcnt lgkmcnt(0)
	v_not_b32_e32 v4, v2
	v_or_b32_e32 v5, 0x80000000, v2
	v_cmp_gt_i32_e32 vcc, 0, v2
	v_and_b32_e32 v7, 0x7fffffff, v3
	v_xor_b32_e32 v2, -1, v3
	v_cndmask_b32_e32 v28, v5, v4, vcc
	ds_read2st64_b32 v[4:5], v87 offset0:2 offset1:3
	v_cmp_gt_i32_e64 s[0:1], 0, v3
	s_waitcnt lgkmcnt(0)
	v_and_b32_e32 v6, 0x7fffffff, v4
	v_xor_b32_e32 v8, -1, v4
	v_pk_add_f32 v[6:7], v[6:7], 0 neg_lo:[1,1] neg_hi:[1,1]
	v_cmp_gt_i32_e32 vcc, 0, v4
	v_cndmask_b32_e64 v3, v7, v2, s[0:1]
	v_and_b32_e32 v9, 0x7fffffff, v5
	v_cndmask_b32_e32 v2, v6, v8, vcc
	ds_read2st64_b32 v[6:7], v87 offset0:4 offset1:5
	v_xor_b32_e32 v4, -1, v5
	v_cmp_gt_i32_e64 s[0:1], 0, v5
	v_max_u32_e32 v10, v28, v3
	v_min3_u32 v11, v28, v3, v2
	s_waitcnt lgkmcnt(0)
	v_and_b32_e32 v8, 0x7fffffff, v6
	v_xor_b32_e32 v12, -1, v6
	v_pk_add_f32 v[8:9], v[8:9], 0 neg_lo:[1,1] neg_hi:[1,1]
	v_cmp_gt_i32_e32 vcc, 0, v6
	v_cndmask_b32_e64 v5, v9, v4, s[0:1]
	v_xor_b32_e32 v6, -1, v7
	v_cndmask_b32_e32 v4, v8, v12, vcc
	ds_read2st64_b32 v[8:9], v87 offset0:6 offset1:7
	v_max3_u32 v12, v10, v2, v5
	v_min3_u32 v13, v11, v5, v4
	v_and_b32_e32 v11, 0x7fffffff, v7
	v_cmp_gt_i32_e64 s[0:1], 0, v7
	s_waitcnt lgkmcnt(0)
	v_and_b32_e32 v10, 0x7fffffff, v8
	v_xor_b32_e32 v14, -1, v8
	v_pk_add_f32 v[10:11], v[10:11], 0 neg_lo:[1,1] neg_hi:[1,1]
	v_cmp_gt_i32_e32 vcc, 0, v8
	v_cndmask_b32_e64 v7, v11, v6, s[0:1]
	v_xor_b32_e32 v8, -1, v9
	v_cndmask_b32_e32 v6, v10, v14, vcc
	ds_read2st64_b32 v[10:11], v87 offset0:8 offset1:9
	v_max3_u32 v14, v12, v4, v7
	v_min3_u32 v15, v13, v7, v6
	v_and_b32_e32 v13, 0x7fffffff, v9
	v_cmp_gt_i32_e64 s[0:1], 0, v9
	s_waitcnt lgkmcnt(0)
	v_and_b32_e32 v12, 0x7fffffff, v10
	v_xor_b32_e32 v16, -1, v10
	v_pk_add_f32 v[12:13], v[12:13], 0 neg_lo:[1,1] neg_hi:[1,1]
	v_cmp_gt_i32_e32 vcc, 0, v10
	v_cndmask_b32_e64 v9, v13, v8, s[0:1]
	v_xor_b32_e32 v10, -1, v11
	v_cndmask_b32_e32 v8, v12, v16, vcc
	ds_read2st64_b32 v[12:13], v87 offset0:10 offset1:11
	v_max3_u32 v16, v14, v6, v9
	v_min3_u32 v17, v15, v9, v8
	v_and_b32_e32 v15, 0x7fffffff, v11
	v_cmp_gt_i32_e64 s[0:1], 0, v11
	s_waitcnt lgkmcnt(0)
	v_and_b32_e32 v14, 0x7fffffff, v12
	v_xor_b32_e32 v18, -1, v12
	v_pk_add_f32 v[14:15], v[14:15], 0 neg_lo:[1,1] neg_hi:[1,1]
	v_cmp_gt_i32_e32 vcc, 0, v12
	v_cndmask_b32_e64 v11, v15, v10, s[0:1]
	v_xor_b32_e32 v12, -1, v13
	v_cndmask_b32_e32 v10, v14, v18, vcc
	ds_read2st64_b32 v[14:15], v87 offset0:12 offset1:13
	v_max3_u32 v18, v16, v8, v11
	v_min3_u32 v19, v17, v11, v10
	v_and_b32_e32 v17, 0x7fffffff, v13
	v_cmp_gt_i32_e64 s[0:1], 0, v13
	s_waitcnt lgkmcnt(0)
	v_and_b32_e32 v16, 0x7fffffff, v14
	v_xor_b32_e32 v20, -1, v14
	v_pk_add_f32 v[16:17], v[16:17], 0 neg_lo:[1,1] neg_hi:[1,1]
	v_cmp_gt_i32_e32 vcc, 0, v14
	v_cndmask_b32_e64 v13, v17, v12, s[0:1]
	v_xor_b32_e32 v14, -1, v15
	v_cndmask_b32_e32 v12, v16, v20, vcc
	ds_read2st64_b32 v[16:17], v87 offset0:14 offset1:15
	v_max3_u32 v20, v18, v10, v13
	v_min3_u32 v21, v19, v13, v12
	v_and_b32_e32 v19, 0x7fffffff, v15
	v_cmp_gt_i32_e64 s[0:1], 0, v15
	s_waitcnt lgkmcnt(0)
	v_and_b32_e32 v18, 0x7fffffff, v16
	v_xor_b32_e32 v22, -1, v16
	v_pk_add_f32 v[18:19], v[18:19], 0 neg_lo:[1,1] neg_hi:[1,1]
	v_cmp_gt_i32_e32 vcc, 0, v16
	v_cndmask_b32_e64 v15, v19, v14, s[0:1]
	v_xor_b32_e32 v16, -1, v17
	v_cndmask_b32_e32 v14, v18, v22, vcc
	ds_read2st64_b32 v[18:19], v87 offset0:16 offset1:17
	v_max3_u32 v22, v20, v12, v15
	v_min3_u32 v23, v21, v15, v14
	v_and_b32_e32 v21, 0x7fffffff, v17
	v_cmp_gt_i32_e64 s[0:1], 0, v17
	s_waitcnt lgkmcnt(0)
	v_and_b32_e32 v20, 0x7fffffff, v18
	v_xor_b32_e32 v24, -1, v18
	v_pk_add_f32 v[20:21], v[20:21], 0 neg_lo:[1,1] neg_hi:[1,1]
	v_cmp_gt_i32_e32 vcc, 0, v18
	v_cndmask_b32_e64 v17, v21, v16, s[0:1]
	v_xor_b32_e32 v18, -1, v19
	v_cndmask_b32_e32 v16, v20, v24, vcc
	ds_read2st64_b32 v[20:21], v87 offset0:18 offset1:19
	v_max3_u32 v24, v22, v14, v17
	v_min3_u32 v25, v23, v17, v16
	v_and_b32_e32 v23, 0x7fffffff, v19
	v_cmp_gt_i32_e64 s[0:1], 0, v19
	s_waitcnt lgkmcnt(0)
	v_and_b32_e32 v22, 0x7fffffff, v20
	v_xor_b32_e32 v26, -1, v20
	v_pk_add_f32 v[22:23], v[22:23], 0 neg_lo:[1,1] neg_hi:[1,1]
	v_cmp_gt_i32_e32 vcc, 0, v20
	v_cndmask_b32_e64 v19, v23, v18, s[0:1]
	v_xor_b32_e32 v20, -1, v21
	v_cndmask_b32_e32 v18, v22, v26, vcc
	ds_read2st64_b32 v[22:23], v87 offset0:20 offset1:21
	v_max3_u32 v26, v24, v16, v19
	v_min3_u32 v27, v25, v19, v18
	v_and_b32_e32 v25, 0x7fffffff, v21
	v_cmp_gt_i32_e64 s[0:1], 0, v21
	s_waitcnt lgkmcnt(0)
; DI unsigned fkey(float f) { unsigned u = __float_as_uint(f); return (u & 0x80000000u) ? ~u : (u | 0x80000000u); }
; template <int NR>
; DI u64 select_wave(float* scw, int nreg, int lane) {
;     ...
; #pragma unroll
;   for (int r = 0; r < NR; ++r) {
;     const unsigned k = fkey(scw[64 * r + lane]);
;     const bool ok = r < nreg;
;     key[r] = ok ? k : 0u;
;     kmin = min(kmin, ok ? k : 0xffffffffu); kmax = max(kmax, key[r]);
;   }
; #pragma unroll
;   for (int o = 1; o < 64; o <<= 1) { kmin = min(kmin, (unsigned)__shfl_xor((int)kmin, o)); kmax = max(kmax, (unsigned)__shfl_xor((int)kmax, o)); }
;   unsigned lo = __builtin_amdgcn_readfirstlane(kmin), hi = __builtin_amdgcn_readfirstlane(kmax);
	v_and_b32_e32 v24, 0x7fffffff, v22
	v_xor_b32_e32 v29, -1, v22
	v_pk_add_f32 v[24:25], v[24:25], 0 neg_lo:[1,1] neg_hi:[1,1]
	v_cmp_gt_i32_e32 vcc, 0, v22
	v_cndmask_b32_e64 v21, v25, v20, s[0:1]
	v_xor_b32_e32 v22, -1, v23
	v_cndmask_b32_e32 v20, v24, v29, vcc
	ds_read2st64_b32 v[24:25], v87 offset0:22 offset1:23
	v_max3_u32 v29, v26, v18, v21
	s_waitcnt vmcnt(10)
	v_min3_u32 v30, v27, v21, v20
	v_and_b32_e32 v27, 0x7fffffff, v23
	v_cmp_gt_i32_e64 s[0:1], 0, v23
	s_waitcnt lgkmcnt(0)
	v_and_b32_e32 v26, 0x7fffffff, v24
	v_xor_b32_e32 v31, -1, v24
	v_pk_add_f32 v[26:27], v[26:27], 0 neg_lo:[1,1] neg_hi:[1,1]
	v_cmp_gt_i32_e32 vcc, 0, v24
	v_cndmask_b32_e64 v23, v27, v22, s[0:1]
	v_xor_b32_e32 v24, -1, v25
	v_cndmask_b32_e32 v22, v26, v31, vcc
	ds_read2st64_b32 v[26:27], v87 offset0:24 offset1:25
	v_min3_u32 v32, v30, v23, v22
	v_and_b32_e32 v31, 0x7fffffff, v25
	v_cmp_gt_i32_e64 s[0:1], 0, v25
	v_max3_u32 v29, v29, v20, v23
	s_waitcnt lgkmcnt(0)
	v_and_b32_e32 v30, 0x7fffffff, v26
	v_pk_add_f32 v[30:31], v[30:31], 0 neg_lo:[1,1] neg_hi:[1,1]
	v_xor_b32_e32 v33, -1, v26
	v_cmp_gt_i32_e32 vcc, 0, v26
	v_cndmask_b32_e64 v25, v31, v24, s[0:1]
	v_max3_u32 v26, v29, v22, v25
	v_cndmask_b32_e32 v24, v30, v33, vcc
	v_not_b32_e32 v29, v27
	v_or_b32_e32 v31, 0x80000000, v27
	v_cmp_gt_i32_e32 vcc, 0, v27
	v_min3_u32 v30, v32, v25, v24
	s_mov_b64 s[0:1], 0
	v_cndmask_b32_e32 v27, v31, v29, vcc
	s_cselect_b64 vcc, -1, 0
	v_cndmask_b32_e32 v29, 0, v27, vcc
	v_min_u32_e32 v27, v30, v27
	v_cndmask_b32_e32 v31, v30, v27, vcc
	v_max3_u32 v32, v26, v24, v29
	ds_read2st64_b32 v[26:27], v87 offset0:26 offset1:27
	s_cmpk_gt_u32 s28, 0x67f
	s_waitcnt lgkmcnt(0)
	v_not_b32_e32 v30, v26
	v_or_b32_e32 v33, 0x80000000, v26
	v_cmp_gt_i32_e32 vcc, 0, v26
	s_nop 1
	v_cndmask_b32_e32 v26, v33, v30, vcc
	s_cselect_b64 vcc, -1, 0
	v_cndmask_b32_e32 v30, 0, v26, vcc
	v_min_u32_e32 v26, v31, v26
	v_cndmask_b32_e32 v26, v31, v26, vcc
	v_not_b32_e32 v31, v27
	v_or_b32_e32 v33, 0x80000000, v27
	v_cmp_gt_i32_e32 vcc, 0, v27
	s_cmpk_gt_u32 s28, 0x6bf
	s_nop 0
	v_cndmask_b32_e32 v27, v33, v31, vcc
	s_cselect_b64 vcc, -1, 0
	v_cndmask_b32_e32 v31, 0, v27, vcc
	v_min_u32_e32 v27, v26, v27
	v_cndmask_b32_e32 v33, v26, v27, vcc
	ds_read2st64_b32 v[26:27], v87 offset0:28 offset1:29
	v_max3_u32 v34, v32, v30, v31
	s_cmpk_gt_u32 s28, 0x6ff
	s_waitcnt lgkmcnt(0)
	v_not_b32_e32 v32, v26
	v_or_b32_e32 v35, 0x80000000, v26
	v_cmp_gt_i32_e32 vcc, 0, v26
	s_nop 1
	v_cndmask_b32_e32 v26, v35, v32, vcc
	s_cselect_b64 vcc, -1, 0
	v_cndmask_b32_e32 v32, 0, v26, vcc
	v_min_u32_e32 v26, v33, v26
	v_cndmask_b32_e32 v26, v33, v26, vcc
	v_not_b32_e32 v33, v27
	v_or_b32_e32 v35, 0x80000000, v27
	v_cmp_gt_i32_e32 vcc, 0, v27
	s_cmpk_gt_u32 s28, 0x73f
	s_nop 0
	v_cndmask_b32_e32 v27, v35, v33, vcc
	s_cselect_b64 vcc, -1, 0
	v_cndmask_b32_e32 v33, 0, v27, vcc
	v_min_u32_e32 v27, v26, v27
	v_cndmask_b32_e32 v35, v26, v27, vcc
	ds_read2st64_b32 v[26:27], v87 offset0:30 offset1:31
	v_max3_u32 v36, v34, v32, v33
	s_cmpk_gt_u32 s28, 0x77f
	s_waitcnt lgkmcnt(0)
	v_not_b32_e32 v34, v26
	v_or_b32_e32 v37, 0x80000000, v26
	v_cmp_gt_i32_e32 vcc, 0, v26
	s_nop 1
	v_cndmask_b32_e32 v26, v37, v34, vcc
	s_cselect_b64 vcc, -1, 0
	v_cndmask_b32_e32 v34, 0, v26, vcc
	v_min_u32_e32 v26, v35, v26
	v_cndmask_b32_e32 v26, v35, v26, vcc
	v_not_b32_e32 v35, v27
	v_or_b32_e32 v37, 0x80000000, v27
	v_cmp_gt_i32_e32 vcc, 0, v27
	s_cmpk_gt_u32 s28, 0x7bf
	s_nop 0
	v_cndmask_b32_e32 v27, v37, v35, vcc
	s_cselect_b64 vcc, -1, 0
	v_cndmask_b32_e32 v35, 0, v27, vcc
	v_min_u32_e32 v27, v26, v27
	v_cndmask_b32_e32 v26, v26, v27, vcc
	v_max3_u32 v27, v36, v34, v35
	s_waitcnt lgkmcnt(0)
	s_nop 1
	v_min_u32_dpp v26, v26, v26 quad_perm:[1,0,3,2] row_mask:0xf bank_mask:0xf
	v_max_u32_dpp v27, v27, v27 quad_perm:[1,0,3,2] row_mask:0xf bank_mask:0xf
	s_nop 0
	v_min_u32_dpp v26, v26, v26 quad_perm:[2,3,0,1] row_mask:0xf bank_mask:0xf
	v_max_u32_dpp v27, v27, v27 quad_perm:[2,3,0,1] row_mask:0xf bank_mask:0xf
	s_nop 0
	v_min_u32_dpp v26, v26, v26 row_half_mirror row_mask:0xf bank_mask:0xf
	v_max_u32_dpp v27, v27, v27 row_half_mirror row_mask:0xf bank_mask:0xf
	s_nop 0
	v_min_u32_dpp v26, v26, v26 row_mirror row_mask:0xf bank_mask:0xf
	v_max_u32_dpp v27, v27, v27 row_mirror row_mask:0xf bank_mask:0xf
	s_nop 0
	v_min_u32_dpp v26, v26, v26 row_bcast:15 row_mask:0xa bank_mask:0xf
	v_max_u32_dpp v27, v27, v27 row_bcast:15 row_mask:0xa bank_mask:0xf
	s_nop 0
	v_min_u32_dpp v26, v26, v26 row_bcast:31 row_mask:0xc bank_mask:0xf
	v_max_u32_dpp v27, v27, v27 row_bcast:31 row_mask:0xc bank_mask:0xf
	s_nop 0
	v_readlane_b32 s23, v26, 63
	v_readlane_b32 s22, v27, 63

; DI unsigned fkey(float f) { unsigned u = __float_as_uint(f); return (u & 0x80000000u) ? ~u : (u | 0x80000000u); }
; template <int NR>
; DI u64 select_wave(float* scw, int nreg, int lane) {
;     ...
; #pragma unroll
;   for (int r = 0; r < NR; ++r) {
;     const unsigned k = fkey(scw[64 * r + lane]);
;     const bool ok = r < nreg;
;     key[r] = ok ? k : 0u;
;     kmin = min(kmin, ok ? k : 0xffffffffu); kmax = max(kmax, key[r]);
;   }
.LBB0_591:
	s_andn2_b64 vcc, exec, s[0:1]
	s_cbranch_vccnz .LBB0_669
	ds_read2st64_b32 v[2:3], v87 offset1:1
	s_cmpk_gt_u32 s28, 0x43f
	s_mov_b32 s5, 0
	s_mov_b32 s44, 0
	s_mov_b32 s6, s4
	s_waitcnt lgkmcnt(0)
	v_not_b32_e32 v4, v2
	v_or_b32_e32 v5, 0x80000000, v2
	v_cmp_gt_i32_e32 vcc, 0, v2
	v_and_b32_e32 v7, 0x7fffffff, v3
	v_xor_b32_e32 v2, -1, v3
	v_cndmask_b32_e32 v18, v5, v4, vcc
	ds_read2st64_b32 v[4:5], v87 offset0:2 offset1:3
	v_cmp_gt_i32_e64 s[0:1], 0, v3
	s_waitcnt lgkmcnt(0)
	v_and_b32_e32 v6, 0x7fffffff, v4
	v_xor_b32_e32 v8, -1, v4
	v_pk_add_f32 v[6:7], v[6:7], 0 neg_lo:[1,1] neg_hi:[1,1]
	v_cmp_gt_i32_e32 vcc, 0, v4
	v_cndmask_b32_e64 v3, v7, v2, s[0:1]
	v_and_b32_e32 v9, 0x7fffffff, v5
	v_cndmask_b32_e32 v2, v6, v8, vcc
	ds_read2st64_b32 v[6:7], v87 offset0:4 offset1:5
	v_xor_b32_e32 v4, -1, v5
	v_cmp_gt_i32_e64 s[0:1], 0, v5
	v_max_u32_e32 v10, v18, v3
	v_min3_u32 v11, v18, v3, v2
	s_waitcnt lgkmcnt(0)
	v_and_b32_e32 v8, 0x7fffffff, v6
	v_xor_b32_e32 v12, -1, v6
	v_pk_add_f32 v[8:9], v[8:9], 0 neg_lo:[1,1] neg_hi:[1,1]
	v_cmp_gt_i32_e32 vcc, 0, v6
	v_cndmask_b32_e64 v5, v9, v4, s[0:1]
	v_xor_b32_e32 v6, -1, v7
	v_cndmask_b32_e32 v4, v8, v12, vcc
	ds_read2st64_b32 v[8:9], v87 offset0:6 offset1:7
	v_max3_u32 v12, v10, v2, v5
	v_min3_u32 v13, v11, v5, v4
	v_and_b32_e32 v11, 0x7fffffff, v7
	v_cmp_gt_i32_e64 s[0:1], 0, v7
	s_waitcnt lgkmcnt(0)
	v_and_b32_e32 v10, 0x7fffffff, v8
	v_xor_b32_e32 v14, -1, v8
	v_pk_add_f32 v[10:11], v[10:11], 0 neg_lo:[1,1] neg_hi:[1,1]
	v_cmp_gt_i32_e32 vcc, 0, v8
	v_cndmask_b32_e64 v7, v11, v6, s[0:1]
	v_xor_b32_e32 v8, -1, v9
	v_cndmask_b32_e32 v6, v10, v14, vcc
	ds_read2st64_b32 v[10:11], v87 offset0:8 offset1:9
	v_max3_u32 v14, v12, v4, v7
	v_min3_u32 v15, v13, v7, v6
	v_and_b32_e32 v13, 0x7fffffff, v9
	v_cmp_gt_i32_e64 s[0:1], 0, v9
	s_waitcnt lgkmcnt(0)
	v_and_b32_e32 v12, 0x7fffffff, v10
	v_xor_b32_e32 v16, -1, v10
	v_pk_add_f32 v[12:13], v[12:13], 0 neg_lo:[1,1] neg_hi:[1,1]
	v_cmp_gt_i32_e32 vcc, 0, v10
	v_cndmask_b32_e64 v9, v13, v8, s[0:1]
	v_xor_b32_e32 v10, -1, v11
	v_cndmask_b32_e32 v8, v12, v16, vcc
	ds_read2st64_b32 v[12:13], v87 offset0:10 offset1:11
	v_max3_u32 v16, v14, v6, v9
	v_min3_u32 v17, v15, v9, v8
	v_and_b32_e32 v15, 0x7fffffff, v11
	v_cmp_gt_i32_e64 s[0:1], 0, v11
	s_waitcnt lgkmcnt(0)
	v_and_b32_e32 v14, 0x7fffffff, v12
	v_xor_b32_e32 v19, -1, v12
	v_pk_add_f32 v[14:15], v[14:15], 0 neg_lo:[1,1] neg_hi:[1,1]
	v_cmp_gt_i32_e32 vcc, 0, v12
	v_cndmask_b32_e64 v11, v15, v10, s[0:1]
	v_xor_b32_e32 v12, -1, v13
	v_cndmask_b32_e32 v10, v14, v19, vcc
	ds_read2st64_b32 v[14:15], v87 offset0:12 offset1:13
	v_max3_u32 v19, v16, v8, v11
	v_min3_u32 v20, v17, v11, v10
	v_and_b32_e32 v17, 0x7fffffff, v13
	v_cmp_gt_i32_e64 s[0:1], 0, v13
	s_waitcnt lgkmcnt(0)
	v_and_b32_e32 v16, 0x7fffffff, v14
	v_xor_b32_e32 v21, -1, v14
	v_pk_add_f32 v[16:17], v[16:17], 0 neg_lo:[1,1] neg_hi:[1,1]
	v_cmp_gt_i32_e32 vcc, 0, v14
	v_cndmask_b32_e64 v13, v17, v12, s[0:1]
	v_xor_b32_e32 v14, -1, v15
	v_cndmask_b32_e32 v12, v16, v21, vcc
	ds_read2st64_b32 v[16:17], v87 offset0:14 offset1:15
	v_min3_u32 v22, v20, v13, v12
	v_and_b32_e32 v21, 0x7fffffff, v15
	v_cmp_gt_i32_e64 s[0:1], 0, v15
	v_max3_u32 v19, v19, v10, v13
	s_waitcnt lgkmcnt(0)
	v_and_b32_e32 v20, 0x7fffffff, v16
	v_xor_b32_e32 v23, -1, v16
	v_pk_add_f32 v[20:21], v[20:21], 0 neg_lo:[1,1] neg_hi:[1,1]
	v_cmp_gt_i32_e32 vcc, 0, v16
	v_cndmask_b32_e64 v15, v21, v14, s[0:1]
	v_xor_b32_e32 v16, -1, v17
	v_cndmask_b32_e32 v14, v20, v23, vcc
	ds_read2st64_b32 v[20:21], v87 offset0:16 offset1:17
	v_min3_u32 v24, v22, v15, v14
	v_and_b32_e32 v23, 0x7fffffff, v17
	v_cmp_gt_i32_e64 s[0:1], 0, v17
	v_max3_u32 v19, v19, v12, v15
	s_waitcnt lgkmcnt(0)
; DI unsigned fkey(float f) { unsigned u = __float_as_uint(f); return (u & 0x80000000u) ? ~u : (u | 0x80000000u); }
; template <int NR>
; DI u64 select_wave(float* scw, int nreg, int lane) {
;     ...
; #pragma unroll
;   for (int r = 0; r < NR; ++r) {
;     const unsigned k = fkey(scw[64 * r + lane]);
;     const bool ok = r < nreg;
;     key[r] = ok ? k : 0u;
;     kmin = min(kmin, ok ? k : 0xffffffffu); kmax = max(kmax, key[r]);
;   }
; #pragma unroll
;   for (int o = 1; o < 64; o <<= 1) { kmin = min(kmin, (unsigned)__shfl_xor((int)kmin, o)); kmax = max(kmax, (unsigned)__shfl_xor((int)kmax, o)); }
;   unsigned lo = __builtin_amdgcn_readfirstlane(kmin), hi = __builtin_amdgcn_readfirstlane(kmax);
	v_and_b32_e32 v22, 0x7fffffff, v20
	v_pk_add_f32 v[22:23], v[22:23], 0 neg_lo:[1,1] neg_hi:[1,1]
	v_xor_b32_e32 v25, -1, v20
	v_cmp_gt_i32_e32 vcc, 0, v20
	v_cndmask_b32_e64 v17, v23, v16, s[0:1]
	v_max3_u32 v20, v19, v14, v17
	v_cndmask_b32_e32 v16, v22, v25, vcc
	v_not_b32_e32 v19, v21
	v_or_b32_e32 v23, 0x80000000, v21
	v_cmp_gt_i32_e32 vcc, 0, v21
	v_min3_u32 v22, v24, v17, v16
	s_mov_b64 s[0:1], 0
	v_cndmask_b32_e32 v21, v23, v19, vcc
	s_cselect_b64 vcc, -1, 0
	v_cndmask_b32_e32 v19, 0, v21, vcc
	v_min_u32_e32 v21, v22, v21
	v_cndmask_b32_e32 v22, v22, v21, vcc
	v_max3_u32 v23, v20, v16, v19
	ds_read2st64_b32 v[20:21], v87 offset0:18 offset1:19
	s_cmpk_gt_u32 s28, 0x47f
	s_waitcnt lgkmcnt(0)
	v_not_b32_e32 v24, v20
	v_or_b32_e32 v25, 0x80000000, v20
	v_cmp_gt_i32_e32 vcc, 0, v20
	s_nop 1
	v_cndmask_b32_e32 v24, v25, v24, vcc
	s_cselect_b64 vcc, -1, 0
	v_cndmask_b32_e32 v20, 0, v24, vcc
	v_min_u32_e32 v24, v22, v24
	v_cndmask_b32_e32 v22, v22, v24, vcc
	v_not_b32_e32 v24, v21
	v_or_b32_e32 v25, 0x80000000, v21
	v_cmp_gt_i32_e32 vcc, 0, v21
	s_cmpk_gt_u32 s28, 0x4bf
	s_nop 0
	v_cndmask_b32_e32 v24, v25, v24, vcc
	s_cselect_b64 vcc, -1, 0
	v_cndmask_b32_e32 v21, 0, v24, vcc
	v_min_u32_e32 v24, v22, v24
	v_cndmask_b32_e32 v24, v22, v24, vcc
	v_max3_u32 v25, v23, v20, v21
	ds_read2st64_b32 v[22:23], v87 offset0:20 offset1:21
	s_cmpk_gt_u32 s28, 0x4ff
	s_waitcnt lgkmcnt(0)
	v_not_b32_e32 v26, v22
	v_or_b32_e32 v27, 0x80000000, v22
	v_cmp_gt_i32_e32 vcc, 0, v22
	s_nop 1
	v_cndmask_b32_e32 v26, v27, v26, vcc
	s_cselect_b64 vcc, -1, 0
	v_cndmask_b32_e32 v22, 0, v26, vcc
	v_min_u32_e32 v26, v24, v26
	v_cndmask_b32_e32 v24, v24, v26, vcc
	v_not_b32_e32 v26, v23
	v_or_b32_e32 v27, 0x80000000, v23
	v_cmp_gt_i32_e32 vcc, 0, v23
	s_cmpk_gt_u32 s28, 0x53f
	s_nop 0
	v_cndmask_b32_e32 v26, v27, v26, vcc
	s_cselect_b64 vcc, -1, 0
	v_cndmask_b32_e32 v23, 0, v26, vcc
	v_min_u32_e32 v26, v24, v26
	v_cndmask_b32_e32 v26, v24, v26, vcc
	v_max3_u32 v27, v25, v22, v23
	ds_read2st64_b32 v[24:25], v87 offset0:22 offset1:23
	s_cmpk_gt_u32 s28, 0x57f
	s_waitcnt lgkmcnt(0)
	v_not_b32_e32 v28, v24
	v_or_b32_e32 v29, 0x80000000, v24
	v_cmp_gt_i32_e32 vcc, 0, v24
	s_nop 1
	v_cndmask_b32_e32 v28, v29, v28, vcc
	s_cselect_b64 vcc, -1, 0
	v_cndmask_b32_e32 v24, 0, v28, vcc
	v_min_u32_e32 v28, v26, v28
	v_cndmask_b32_e32 v26, v26, v28, vcc
	v_not_b32_e32 v28, v25
	v_or_b32_e32 v29, 0x80000000, v25
	v_cmp_gt_i32_e32 vcc, 0, v25
	s_cmpk_gt_u32 s28, 0x5bf
	s_nop 0
	v_cndmask_b32_e32 v28, v29, v28, vcc
	s_cselect_b64 vcc, -1, 0
	v_cndmask_b32_e32 v25, 0, v28, vcc
	v_min_u32_e32 v28, v26, v28
	v_cndmask_b32_e32 v26, v26, v28, vcc
	v_max3_u32 v27, v27, v24, v25
	s_waitcnt vmcnt(10)
	s_waitcnt lgkmcnt(0)
	s_nop 1
	v_min_u32_dpp v26, v26, v26 quad_perm:[1,0,3,2] row_mask:0xf bank_mask:0xf
	v_max_u32_dpp v27, v27, v27 quad_perm:[1,0,3,2] row_mask:0xf bank_mask:0xf
	s_nop 0
	v_min_u32_dpp v26, v26, v26 quad_perm:[2,3,0,1] row_mask:0xf bank_mask:0xf
	v_max_u32_dpp v27, v27, v27 quad_perm:[2,3,0,1] row_mask:0xf bank_mask:0xf
	s_nop 0
	v_min_u32_dpp v26, v26, v26 row_half_mirror row_mask:0xf bank_mask:0xf
	v_max_u32_dpp v27, v27, v27 row_half_mirror row_mask:0xf bank_mask:0xf
	s_nop 0
	v_min_u32_dpp v26, v26, v26 row_mirror row_mask:0xf bank_mask:0xf
	v_max_u32_dpp v27, v27, v27 row_mirror row_mask:0xf bank_mask:0xf
	s_nop 0
	v_min_u32_dpp v26, v26, v26 row_bcast:15 row_mask:0xa bank_mask:0xf
	v_max_u32_dpp v27, v27, v27 row_bcast:15 row_mask:0xa bank_mask:0xf
	s_nop 0
	v_min_u32_dpp v26, v26, v26 row_bcast:31 row_mask:0xc bank_mask:0xf
	v_max_u32_dpp v27, v27, v27 row_bcast:31 row_mask:0xc bank_mask:0xf
	s_nop 0
	v_readlane_b32 s23, v26, 63
	v_readlane_b32 s22, v27, 63

; DI unsigned fkey(float f) { unsigned u = __float_as_uint(f); return (u & 0x80000000u) ? ~u : (u | 0x80000000u); }
; template <int NR>
; DI u64 select_wave(float* scw, int nreg, int lane) {
;     ...
; #pragma unroll
;   for (int r = 0; r < NR; ++r) {
;     const unsigned k = fkey(scw[64 * r + lane]);
;     const bool ok = r < nreg;
;     key[r] = ok ? k : 0u;
;     kmin = min(kmin, ok ? k : 0xffffffffu); kmax = max(kmax, key[r]);
;   }
; #pragma unroll
;   for (int o = 1; o < 64; o <<= 1) { kmin = min(kmin, (unsigned)__shfl_xor((int)kmin, o)); kmax = max(kmax, (unsigned)__shfl_xor((int)kmax, o)); }
;   unsigned lo = __builtin_amdgcn_readfirstlane(kmin), hi = __builtin_amdgcn_readfirstlane(kmax);
.LBB0_670:
	s_andn2_b64 vcc, exec, s[0:1]
	s_cbranch_vccnz .LBB0_732
	ds_read2st64_b32 v[2:3], v87 offset1:1
	s_cmpk_gt_u32 s28, 0x23f
	s_mov_b32 s5, 0
	s_mov_b32 s44, 0
	s_waitcnt lgkmcnt(0)
	v_not_b32_e32 v4, v2
	v_or_b32_e32 v5, 0x80000000, v2
	v_cmp_gt_i32_e32 vcc, 0, v2
	v_and_b32_e32 v7, 0x7fffffff, v3
	v_xor_b32_e32 v2, -1, v3
	v_cndmask_b32_e32 v10, v5, v4, vcc
	ds_read2st64_b32 v[4:5], v87 offset0:2 offset1:3
	v_cmp_gt_i32_e64 s[0:1], 0, v3
	s_waitcnt lgkmcnt(0)
	v_and_b32_e32 v6, 0x7fffffff, v4
	v_xor_b32_e32 v8, -1, v4
	v_pk_add_f32 v[6:7], v[6:7], 0 neg_lo:[1,1] neg_hi:[1,1]
	v_cmp_gt_i32_e32 vcc, 0, v4
	v_cndmask_b32_e64 v3, v7, v2, s[0:1]
	v_and_b32_e32 v9, 0x7fffffff, v5
	v_cndmask_b32_e32 v2, v6, v8, vcc
	ds_read2st64_b32 v[6:7], v87 offset0:4 offset1:5
	v_xor_b32_e32 v4, -1, v5
	v_cmp_gt_i32_e64 s[0:1], 0, v5
	v_min3_u32 v12, v10, v3, v2
	v_max_u32_e32 v11, v10, v3
	s_waitcnt lgkmcnt(0)
	v_and_b32_e32 v8, 0x7fffffff, v6
	v_xor_b32_e32 v13, -1, v6
	v_pk_add_f32 v[8:9], v[8:9], 0 neg_lo:[1,1] neg_hi:[1,1]
	v_cmp_gt_i32_e32 vcc, 0, v6
	v_cndmask_b32_e64 v5, v9, v4, s[0:1]
	v_xor_b32_e32 v6, -1, v7
	v_cndmask_b32_e32 v4, v8, v13, vcc
	ds_read2st64_b32 v[8:9], v87 offset0:6 offset1:7
	v_min3_u32 v14, v12, v5, v4
	v_and_b32_e32 v13, 0x7fffffff, v7
	v_cmp_gt_i32_e64 s[0:1], 0, v7
	v_max3_u32 v11, v11, v2, v5
	s_waitcnt lgkmcnt(0)
	v_and_b32_e32 v12, 0x7fffffff, v8
	v_xor_b32_e32 v15, -1, v8
	v_pk_add_f32 v[12:13], v[12:13], 0 neg_lo:[1,1] neg_hi:[1,1]
	v_cmp_gt_i32_e32 vcc, 0, v8
	v_cndmask_b32_e64 v7, v13, v6, s[0:1]
	v_xor_b32_e32 v8, -1, v9
	v_cndmask_b32_e32 v6, v12, v15, vcc
	ds_read2st64_b32 v[12:13], v87 offset0:8 offset1:9
	v_min3_u32 v16, v14, v7, v6
	v_and_b32_e32 v15, 0x7fffffff, v9
	v_cmp_gt_i32_e64 s[0:1], 0, v9
	v_max3_u32 v11, v11, v4, v7
	s_waitcnt lgkmcnt(0)
	v_and_b32_e32 v14, 0x7fffffff, v12
	v_pk_add_f32 v[14:15], v[14:15], 0 neg_lo:[1,1] neg_hi:[1,1]
	v_xor_b32_e32 v17, -1, v12
	v_cmp_gt_i32_e32 vcc, 0, v12
	v_cndmask_b32_e64 v9, v15, v8, s[0:1]
	v_max3_u32 v12, v11, v6, v9
	v_cndmask_b32_e32 v8, v14, v17, vcc
	v_not_b32_e32 v11, v13
	v_or_b32_e32 v15, 0x80000000, v13
	v_cmp_gt_i32_e32 vcc, 0, v13
	v_min3_u32 v14, v16, v9, v8
	s_mov_b64 s[0:1], 0
	v_cndmask_b32_e32 v13, v15, v11, vcc
	s_cselect_b64 vcc, -1, 0
	v_cndmask_b32_e32 v11, 0, v13, vcc
	v_min_u32_e32 v13, v14, v13
	v_cndmask_b32_e32 v14, v14, v13, vcc
	v_max3_u32 v15, v12, v8, v11
	ds_read2st64_b32 v[12:13], v87 offset0:10 offset1:11
	s_cmpk_gt_u32 s28, 0x27f
	s_waitcnt lgkmcnt(0)
	v_not_b32_e32 v16, v12
	v_or_b32_e32 v17, 0x80000000, v12
	v_cmp_gt_i32_e32 vcc, 0, v12
	s_nop 1
	v_cndmask_b32_e32 v16, v17, v16, vcc
	s_cselect_b64 vcc, -1, 0
	v_cndmask_b32_e32 v12, 0, v16, vcc
	v_min_u32_e32 v16, v14, v16
	v_cndmask_b32_e32 v14, v14, v16, vcc
	v_not_b32_e32 v16, v13
	v_or_b32_e32 v17, 0x80000000, v13
	v_cmp_gt_i32_e32 vcc, 0, v13
	s_cmpk_gt_u32 s28, 0x2bf
	s_nop 0
	v_cndmask_b32_e32 v16, v17, v16, vcc
	s_cselect_b64 vcc, -1, 0
	v_cndmask_b32_e32 v13, 0, v16, vcc
	v_min_u32_e32 v16, v14, v16
	v_cndmask_b32_e32 v16, v14, v16, vcc
	v_max3_u32 v17, v15, v12, v13
	ds_read2st64_b32 v[14:15], v87 offset0:12 offset1:13
	s_cmpk_gt_u32 s28, 0x2ff
	s_waitcnt lgkmcnt(0)
	v_not_b32_e32 v18, v14
	v_or_b32_e32 v19, 0x80000000, v14
	v_cmp_gt_i32_e32 vcc, 0, v14
	s_nop 1
	v_cndmask_b32_e32 v18, v19, v18, vcc
	s_cselect_b64 vcc, -1, 0
	v_cndmask_b32_e32 v14, 0, v18, vcc
	v_min_u32_e32 v18, v16, v18
	v_cndmask_b32_e32 v16, v16, v18, vcc
	v_not_b32_e32 v18, v15
	v_or_b32_e32 v19, 0x80000000, v15
	v_cmp_gt_i32_e32 vcc, 0, v15
	s_cmpk_gt_u32 s28, 0x33f
	s_nop 0
	v_cndmask_b32_e32 v18, v19, v18, vcc
	s_cselect_b64 vcc, -1, 0
	v_cndmask_b32_e32 v15, 0, v18, vcc
	v_min_u32_e32 v18, v16, v18
	v_cndmask_b32_e32 v18, v16, v18, vcc
	v_max3_u32 v19, v17, v14, v15
	ds_read2st64_b32 v[16:17], v87 offset0:14 offset1:15
	s_cmpk_gt_u32 s28, 0x37f
	s_waitcnt lgkmcnt(0)
	v_not_b32_e32 v20, v16
	v_or_b32_e32 v21, 0x80000000, v16
	v_cmp_gt_i32_e32 vcc, 0, v16
	s_nop 1
	v_cndmask_b32_e32 v20, v21, v20, vcc
	s_cselect_b64 vcc, -1, 0
	v_cndmask_b32_e32 v16, 0, v20, vcc
	v_min_u32_e32 v20, v18, v20
	v_cndmask_b32_e32 v18, v18, v20, vcc
	v_not_b32_e32 v20, v17
	v_or_b32_e32 v21, 0x80000000, v17
	v_cmp_gt_i32_e32 vcc, 0, v17
	s_cmpk_gt_u32 s28, 0x3bf
	s_nop 0
	v_cndmask_b32_e32 v20, v21, v20, vcc
	s_cselect_b64 vcc, -1, 0
	v_cndmask_b32_e32 v17, 0, v20, vcc
	v_min_u32_e32 v20, v18, v20
	v_cndmask_b32_e32 v18, v18, v20, vcc
	v_max3_u32 v19, v19, v16, v17
	s_waitcnt lgkmcnt(0)
	s_nop 1
	v_min_u32_dpp v18, v18, v18 quad_perm:[1,0,3,2] row_mask:0xf bank_mask:0xf
	v_max_u32_dpp v19, v19, v19 quad_perm:[1,0,3,2] row_mask:0xf bank_mask:0xf
	s_nop 0
	v_min_u32_dpp v18, v18, v18 quad_perm:[2,3,0,1] row_mask:0xf bank_mask:0xf
	v_max_u32_dpp v19, v19, v19 quad_perm:[2,3,0,1] row_mask:0xf bank_mask:0xf
	s_nop 0
	v_min_u32_dpp v18, v18, v18 row_half_mirror row_mask:0xf bank_mask:0xf
	v_max_u32_dpp v19, v19, v19 row_half_mirror row_mask:0xf bank_mask:0xf
	s_nop 0
	v_min_u32_dpp v18, v18, v18 row_mirror row_mask:0xf bank_mask:0xf
	v_max_u32_dpp v19, v19, v19 row_mirror row_mask:0xf bank_mask:0xf
	s_nop 0
	v_min_u32_dpp v18, v18, v18 row_bcast:15 row_mask:0xa bank_mask:0xf
	v_max_u32_dpp v19, v19, v19 row_bcast:15 row_mask:0xa bank_mask:0xf
	s_nop 0
	v_min_u32_dpp v18, v18, v18 row_bcast:31 row_mask:0xc bank_mask:0xf
	v_max_u32_dpp v19, v19, v19 row_bcast:31 row_mask:0xc bank_mask:0xf
	s_nop 0
	v_readlane_b32 s23, v18, 63
	v_readlane_b32 s22, v19, 63

; DI unsigned fkey(float f) { unsigned u = __float_as_uint(f); return (u & 0x80000000u) ? ~u : (u | 0x80000000u); }
; DI float funkey(unsigned k) { return __uint_as_float((k & 0x80000000u) ? (k ^ 0x80000000u) : ~k); }
; template <int NR>
; DI u64 select_wave(float* scw, int nreg, int lane) {
;     ...
; #pragma unroll
;   for (int r = 0; r < NR; ++r) {
;     const unsigned k = fkey(scw[64 * r + lane]);
;     const bool ok = r < nreg;
;     key[r] = ok ? k : 0u;
;     kmin = min(kmin, ok ? k : 0xffffffffu); kmax = max(kmax, key[r]);
;   }
; #pragma unroll
;   for (int o = 1; o < 64; o <<= 1) { kmin = min(kmin, (unsigned)__shfl_xor((int)kmin, o)); kmax = max(kmax, (unsigned)__shfl_xor((int)kmax, o)); }
;   unsigned lo = __builtin_amdgcn_readfirstlane(kmin), hi = __builtin_amdgcn_readfirstlane(kmax);
;   int clo = 64 * nreg, chi = 0;
;   bool exact = false;
;   int iter = 0;
;   while (lo < hi && clo - chi > 512) {
;     unsigned mid = fkey(0.5f * (funkey(lo) + funkey(hi)));
;     if (iter >= 16) mid = lo + ((hi - lo + 1u) >> 1);
;     if (mid <= lo) mid = lo + 1;
;     if (mid > hi) mid = hi;
;     ++iter;
;     int cnt = 0;
; #pragma unroll
;     for (int r = 0; r < NR; ++r) cnt += __builtin_popcountll(__builtin_amdgcn_ballot_w64(key[r] >= mid));
;     if (cnt >= 256) { lo = mid; clo = cnt; if (cnt == 256) { exact = true; break; } }
;     else { hi = mid - 1; chi = cnt; }
;   }
;   if (!exact && lo < hi) {
;     unsigned* cand = reinterpret_cast<unsigned*>(scw);
;     int base = 0;
; #pragma unroll
;     for (int r = 0; r < NR; ++r) {
;       const bool pred = (key[r] >= lo) && (key[r] <= hi);
;       const u64 bal = __builtin_amdgcn_ballot_w64(pred);
;       const int pos = base + __builtin_amdgcn_mbcnt_hi((unsigned)(bal >> 32), __builtin_amdgcn_mbcnt_lo((unsigned)bal, 0u));
;       if (pred) cand[pos] = key[r];
.LBB0_733:
	s_andn2_b64 vcc, exec, s[0:1]
	s_cbranch_vccnz .LBB0_759
	ds_read2st64_b32 v[2:3], v87 offset1:1
	s_cmp_eq_u32 s47, 0
	s_waitcnt lgkmcnt(0)
	v_not_b32_e32 v4, v2
	v_or_b32_e32 v5, 0x80000000, v2
	v_cmp_gt_i32_e32 vcc, 0, v2
	s_nop 1
	v_cndmask_b32_e32 v2, v5, v4, vcc
	v_not_b32_e32 v4, v3
	v_or_b32_e32 v5, 0x80000000, v3
	v_cmp_gt_i32_e32 vcc, 0, v3
	s_nop 1
	v_cndmask_b32_e32 v4, v5, v4, vcc
	s_cselect_b64 vcc, -1, 0
	v_cndmask_b32_e64 v3, v4, 0, vcc
	v_min_u32_e32 v4, v2, v4
	v_cndmask_b32_e32 v6, v4, v2, vcc
	ds_read2st64_b32 v[4:5], v87 offset0:2 offset1:3
	v_max_u32_e32 v10, v2, v3
	s_cmpk_gt_u32 s28, 0x13f
	s_waitcnt lgkmcnt(0)
	v_not_b32_e32 v7, v4
	v_or_b32_e32 v8, 0x80000000, v4
	v_cmp_gt_i32_e32 vcc, 0, v4
	v_and_b32_e32 v9, 0x7fffffff, v5
	v_xor_b32_e32 v12, -1, v5
	v_cndmask_b32_e32 v4, v8, v7, vcc
	v_min_u32_e32 v11, v6, v4
	ds_read2st64_b32 v[6:7], v87 offset0:4 offset1:5
	v_cmp_gt_i32_e64 s[0:1], 0, v5
	s_waitcnt lgkmcnt(0)
	v_and_b32_e32 v8, 0x7fffffff, v6
	v_xor_b32_e32 v13, -1, v6
	v_pk_add_f32 v[8:9], v[8:9], 0 neg_lo:[1,1] neg_hi:[1,1]
	v_cmp_gt_i32_e32 vcc, 0, v6
	v_cndmask_b32_e64 v6, v9, v12, s[0:1]
	s_mov_b64 s[0:1], 0
	v_cndmask_b32_e32 v5, v8, v13, vcc
	v_max3_u32 v8, v10, v4, v6
	v_min3_u32 v9, v11, v6, v5
	v_not_b32_e32 v10, v7
	v_or_b32_e32 v11, 0x80000000, v7
	v_cmp_gt_i32_e32 vcc, 0, v7
	s_nop 1
	v_cndmask_b32_e32 v10, v11, v10, vcc
	s_cselect_b64 vcc, -1, 0
	v_cndmask_b32_e32 v7, 0, v10, vcc
	v_min_u32_e32 v10, v9, v10
	v_cndmask_b32_e32 v10, v9, v10, vcc
	v_max3_u32 v11, v8, v5, v7
	ds_read2st64_b32 v[8:9], v87 offset0:6 offset1:7
	s_cmpk_gt_u32 s28, 0x17f
	s_waitcnt lgkmcnt(0)
	v_not_b32_e32 v12, v8
	v_or_b32_e32 v13, 0x80000000, v8
	v_cmp_gt_i32_e32 vcc, 0, v8
	s_nop 1
	v_cndmask_b32_e32 v12, v13, v12, vcc
	s_cselect_b64 vcc, -1, 0
	v_cndmask_b32_e32 v8, 0, v12, vcc
	v_min_u32_e32 v12, v10, v12
	v_cndmask_b32_e32 v10, v10, v12, vcc
	v_not_b32_e32 v12, v9
	v_or_b32_e32 v13, 0x80000000, v9
	v_cmp_gt_i32_e32 vcc, 0, v9
	s_cmpk_gt_u32 s28, 0x1bf
	s_nop 0
	v_cndmask_b32_e32 v12, v13, v12, vcc
	s_cselect_b64 vcc, -1, 0
	v_cndmask_b32_e32 v9, 0, v12, vcc
	v_min_u32_e32 v12, v10, v12
	v_cndmask_b32_e32 v10, v10, v12, vcc
	v_max3_u32 v11, v11, v8, v9
	s_waitcnt lgkmcnt(0)
	s_nop 1
	v_min_u32_dpp v10, v10, v10 quad_perm:[1,0,3,2] row_mask:0xf bank_mask:0xf
	v_max_u32_dpp v11, v11, v11 quad_perm:[1,0,3,2] row_mask:0xf bank_mask:0xf
	s_nop 0
	v_min_u32_dpp v10, v10, v10 quad_perm:[2,3,0,1] row_mask:0xf bank_mask:0xf
	v_max_u32_dpp v11, v11, v11 quad_perm:[2,3,0,1] row_mask:0xf bank_mask:0xf
	s_nop 0
	v_min_u32_dpp v10, v10, v10 row_half_mirror row_mask:0xf bank_mask:0xf
	v_max_u32_dpp v11, v11, v11 row_half_mirror row_mask:0xf bank_mask:0xf
	s_nop 0
	v_min_u32_dpp v10, v10, v10 row_mirror row_mask:0xf bank_mask:0xf
	v_max_u32_dpp v11, v11, v11 row_mirror row_mask:0xf bank_mask:0xf
	s_nop 0
	v_min_u32_dpp v10, v10, v10 row_bcast:15 row_mask:0xa bank_mask:0xf
	v_max_u32_dpp v11, v11, v11 row_bcast:15 row_mask:0xa bank_mask:0xf
	s_nop 0
	v_min_u32_dpp v10, v10, v10 row_bcast:31 row_mask:0xc bank_mask:0xf
	v_max_u32_dpp v11, v11, v11 row_bcast:31 row_mask:0xc bank_mask:0xf
	s_nop 0
	v_readlane_b32 s23, v10, 63
	v_readlane_b32 s22, v11, 63
	s_cmp_ge_u32 s23, s22
	s_cbranch_scc1 .LBB0_755
	v_cmp_le_u32_e32 vcc, s23, v2
	v_cmp_ge_u32_e64 s[0:1], s22, v2
	s_and_b64 s[2:3], vcc, s[0:1]
	s_mov_b64 vcc, s[2:3]
	s_and_saveexec_b64 s[0:1], s[2:3]
	s_nop 0
	v_mbcnt_lo_u32_b32 v10, vcc_lo, 0
	v_mbcnt_hi_u32_b32 v10, vcc_hi, v10
	v_lshl_add_u32 v10, v10, 2, s15
	ds_write_b32 v10, v2
	s_or_b64 exec, exec, s[0:1]
	s_bcnt1_i32_b64 s2, vcc
	v_cmp_le_u32_e32 vcc, s23, v3
	v_cmp_ge_u32_e64 s[0:1], s22, v3
	s_and_b64 s[4:5], vcc, s[0:1]
	s_mov_b64 vcc, s[4:5]
	s_and_saveexec_b64 s[0:1], s[4:5]
	v_mbcnt_lo_u32_b32 v10, vcc_lo, 0
	s_lshl_b32 s3, s2, 2
	v_mbcnt_hi_u32_b32 v10, vcc_hi, v10
	s_add_i32 s3, s3, s15
	v_lshl_add_u32 v10, v10, 2, s3
	ds_write_b32 v10, v3
